# S5 pass-2 recurrence rewritten as in-place scalar v_fma_f32 chain (no packed ops or register shuffles) on top of previous edits
# speedup vs baseline: 1.0392x; 1.0051x over previous
.LBB0_185:
	s_or_b64 exec, exec, s[2:3]
	s_lshl_b32 s24, s14, 2
	v_lshl_add_u64 v[0:1], v[160:161], 0, s[24:25]
	s_waitcnt vmcnt(0)
	global_load_dwordx4 v[96:99], v[0:1], off
	global_load_dwordx4 v[100:103], v[0:1], off offset:32
	s_lshl_b32 s2, s66, 7
	s_and_b32 s2, s2, 0xffffe000
	v_or3_b32 v120, s2, v197, v155
	v_ashrrev_i32_e32 v121, 31, v120
	v_lshl_add_u64 v[0:1], v[168:169], 0, v[120:121]
	v_lshl_add_u64 v[2:3], v[166:167], 0, v[120:121]
	v_lshl_add_u64 v[4:5], v[164:165], 0, v[120:121]
	v_lshl_add_u64 v[6:7], v[162:163], 0, v[120:121]
	v_cndmask_b32_e64 v1, v1, 0, s[10:11]
	v_cndmask_b32_e64 v0, v0, v154, s[10:11]
	v_cndmask_b32_e64 v3, v3, 0, s[8:9]
	v_cndmask_b32_e64 v2, v2, v154, s[8:9]
	v_cndmask_b32_e64 v5, v5, 0, s[6:7]
	v_cndmask_b32_e64 v4, v4, v154, s[6:7]
	v_cndmask_b32_e64 v7, v7, 0, s[4:5]
	v_cndmask_b32_e64 v6, v6, v154, s[4:5]
	v_lshlrev_b64 v[0:1], 11, v[0:1]
	v_mov_b32_e32 v185, v149
	v_lshlrev_b64 v[2:3], 11, v[2:3]
	v_lshlrev_b64 v[4:5], 11, v[4:5]
	v_lshlrev_b64 v[6:7], 11, v[6:7]
	v_lshl_add_u64 v[0:1], s[84:85], 0, v[0:1]
	v_lshl_add_u64 v[2:3], s[84:85], 0, v[2:3]
	v_lshl_add_u64 v[4:5], s[84:85], 0, v[4:5]
	v_lshl_add_u64 v[6:7], s[84:85], 0, v[6:7]
	v_lshl_add_u64 v[0:1], v[0:1], 0, v[184:185]
	v_lshl_add_u64 v[2:3], v[2:3], 0, v[184:185]
	v_lshl_add_u64 v[4:5], v[4:5], 0, v[184:185]
	v_lshl_add_u64 v[6:7], v[6:7], 0, v[184:185]
	s_lshl_b32 s24, s14, 1
	s_cmp_lt_u32 s66, 64
	s_cselect_b64 s[2:3], -1, 0
	v_lshl_add_u64 v[126:127], v[170:171], 0, s[24:25]
	v_lshl_add_u64 v[184:185], s[84:85], 0, v[184:185]
	s_and_b64 s[50:51], s[2:3], s[12:13]
	s_mov_b32 s24, s28
	s_waitcnt vmcnt(0)
	global_load_dwordx4 v[112:115], v[0:1], off
	global_load_dwordx4 v[116:119], v[2:3], off
	global_load_dwordx4 v[104:107], v[4:5], off
	global_load_dwordx4 v[108:111], v[6:7], off
	v_add_u32_e32 v0, s15, v205
	v_ashrrev_i32_e32 v1, 31, v0
	v_lshl_add_u64 v[122:123], s[42:43], 0, v[0:1]
	v_lshl_add_u64 v[124:125], s[44:45], 0, v[0:1]
	v_mov_b32_e32 v186, v48
	v_mov_b32_e32 v187, v50
	v_mov_b32_e32 v188, v49
	v_mov_b32_e32 v189, v51
	v_mov_b32_e32 v240, 0xbdd2d3e7
	s_waitcnt vmcnt(0)
	s_branch .LBB0_188

.LBB0_188:
	s_waitcnt vmcnt(9)
	v_mfma_f32_32x32x16_bf16 v[0:15], v[108:111], v[128:131], 0
	v_mfma_f32_32x32x16_bf16 v[16:31], v[108:111], v[132:135], 0
	v_mfma_f32_32x32x16_bf16 v[48:63], v[108:111], v[136:139], 0
	v_mfma_f32_32x32x16_bf16 v[32:47], v[108:111], v[140:143], 0
	v_add_u32_e32 v148, v200, v150
	ds_write_b128 v148, v[108:111] offset:8192
	s_cmp_gt_i32 s24, 0
	s_cselect_b64 s[2:3], -1, 0
	s_or_b64 s[14:15], s[2:3], s[50:51]
	s_nop 7
	v_fma_f32 v0, v172, v186, v0
	v_fma_f32 v16, v174, v188, v16
	v_fma_f32 v48, v172, v187, v48
	v_fma_f32 v32, v174, v189, v32
	v_fma_f32 v0, -v173, v187, v0
	v_fma_f32 v16, -v175, v189, v16
	v_fma_f32 v48, v173, v186, v48
	v_fma_f32 v32, v175, v188, v32
	v_fma_f32 v1, v172, v0, v1
	v_fma_f32 v17, v174, v16, v17
	v_fma_f32 v49, v172, v48, v49
	v_fma_f32 v33, v174, v32, v33
	v_fma_f32 v1, -v173, v48, v1
	v_fma_f32 v17, -v175, v32, v17
	v_fma_f32 v49, v173, v0, v49
	v_fma_f32 v33, v175, v16, v33
	v_fma_f32 v2, v172, v1, v2
	v_fma_f32 v18, v174, v17, v18
	v_fma_f32 v50, v172, v49, v50
	v_fma_f32 v34, v174, v33, v34
	v_fma_f32 v2, -v173, v49, v2
	v_fma_f32 v18, -v175, v33, v18
	v_fma_f32 v50, v173, v1, v50
	v_fma_f32 v34, v175, v17, v34
	v_fma_f32 v3, v172, v2, v3
	v_fma_f32 v19, v174, v18, v19
	v_fma_f32 v51, v172, v50, v51
	v_fma_f32 v35, v174, v34, v35
	v_fma_f32 v3, -v173, v50, v3
	v_fma_f32 v19, -v175, v34, v19
	v_fma_f32 v51, v173, v2, v51
	v_fma_f32 v35, v175, v18, v35
	v_cvt_pk_bf16_f32 v190, v0, v1
	v_cvt_pk_bf16_f32 v191, v2, v3
	v_cvt_pk_bf16_f32 v192, v16, v17
	v_cvt_pk_bf16_f32 v193, v18, v19
	ds_write2st64_b64 v207, v[190:191], v[192:193] offset1:4
	v_cvt_pk_bf16_f32 v212, v48, v49
	v_cvt_pk_bf16_f32 v213, v50, v51
	v_cvt_pk_bf16_f32 v214, v32, v33
	v_cvt_pk_bf16_f32 v215, v34, v35
	ds_write2st64_b64 v207, v[212:213], v[214:215] offset0:8 offset1:12
	v_fma_f32 v4, v172, v3, v4
	v_fma_f32 v20, v174, v19, v20
	v_fma_f32 v52, v172, v51, v52
	v_fma_f32 v36, v174, v35, v36
	v_fma_f32 v4, -v173, v51, v4
	v_fma_f32 v20, -v175, v35, v20
	v_fma_f32 v52, v173, v3, v52
	v_fma_f32 v36, v175, v19, v36
	v_fma_f32 v5, v172, v4, v5
	v_fma_f32 v21, v174, v20, v21
	v_fma_f32 v53, v172, v52, v53
	v_fma_f32 v37, v174, v36, v37
	v_fma_f32 v5, -v173, v52, v5
	v_fma_f32 v21, -v175, v36, v21
	v_fma_f32 v53, v173, v4, v53
	v_fma_f32 v37, v175, v20, v37
	v_fma_f32 v6, v172, v5, v6
	v_fma_f32 v22, v174, v21, v22
	v_fma_f32 v54, v172, v53, v54
	v_fma_f32 v38, v174, v37, v38
	v_fma_f32 v6, -v173, v53, v6
	v_fma_f32 v22, -v175, v37, v22
	v_fma_f32 v54, v173, v5, v54
	v_fma_f32 v38, v175, v21, v38
	v_fma_f32 v7, v172, v6, v7
	v_fma_f32 v23, v174, v22, v23
	v_fma_f32 v55, v172, v54, v55
	v_fma_f32 v39, v174, v38, v39
	v_fma_f32 v7, -v173, v54, v7
	v_fma_f32 v23, -v175, v38, v23
	v_fma_f32 v55, v173, v6, v55
	v_fma_f32 v39, v175, v22, v39
	v_cvt_pk_bf16_f32 v190, v4, v5
	v_cvt_pk_bf16_f32 v191, v6, v7
	v_cvt_pk_bf16_f32 v192, v20, v21
	v_cvt_pk_bf16_f32 v193, v22, v23
	ds_write2st64_b64 v208, v[190:191], v[192:193] offset1:4
	v_cvt_pk_bf16_f32 v212, v52, v53
	v_cvt_pk_bf16_f32 v213, v54, v55
	v_cvt_pk_bf16_f32 v214, v36, v37
	v_cvt_pk_bf16_f32 v215, v38, v39
	ds_write2st64_b64 v208, v[212:213], v[214:215] offset0:8 offset1:12
	v_fma_f32 v8, v172, v7, v8
	v_fma_f32 v24, v174, v23, v24
	v_fma_f32 v56, v172, v55, v56
	v_fma_f32 v40, v174, v39, v40
	v_fma_f32 v8, -v173, v55, v8
	v_fma_f32 v24, -v175, v39, v24
	v_fma_f32 v56, v173, v7, v56
	v_fma_f32 v40, v175, v23, v40
	v_fma_f32 v9, v172, v8, v9
	v_fma_f32 v25, v174, v24, v25
	v_fma_f32 v57, v172, v56, v57
	v_fma_f32 v41, v174, v40, v41
	v_fma_f32 v9, -v173, v56, v9
	v_fma_f32 v25, -v175, v40, v25
	v_fma_f32 v57, v173, v8, v57
	v_fma_f32 v41, v175, v24, v41
	v_fma_f32 v10, v172, v9, v10
	v_fma_f32 v26, v174, v25, v26
	v_fma_f32 v58, v172, v57, v58
	v_fma_f32 v42, v174, v41, v42
	v_fma_f32 v10, -v173, v57, v10
	v_fma_f32 v26, -v175, v41, v26
	v_fma_f32 v58, v173, v9, v58
	v_fma_f32 v42, v175, v25, v42
	v_fma_f32 v11, v172, v10, v11
	v_fma_f32 v27, v174, v26, v27
	v_fma_f32 v59, v172, v58, v59
	v_fma_f32 v43, v174, v42, v43
	v_fma_f32 v11, -v173, v58, v11
	v_fma_f32 v27, -v175, v42, v27
	v_fma_f32 v59, v173, v10, v59
	v_fma_f32 v43, v175, v26, v43
	v_cvt_pk_bf16_f32 v190, v8, v9
	v_cvt_pk_bf16_f32 v191, v10, v11
	v_cvt_pk_bf16_f32 v192, v24, v25
	v_cvt_pk_bf16_f32 v193, v26, v27
	ds_write2st64_b64 v209, v[190:191], v[192:193] offset1:4
	v_cvt_pk_bf16_f32 v212, v56, v57
	v_cvt_pk_bf16_f32 v213, v58, v59
	v_cvt_pk_bf16_f32 v214, v40, v41
	v_cvt_pk_bf16_f32 v215, v42, v43
	ds_write2st64_b64 v209, v[212:213], v[214:215] offset0:8 offset1:12
	v_fma_f32 v12, v172, v11, v12
	v_fma_f32 v28, v174, v27, v28
	v_fma_f32 v60, v172, v59, v60
	v_fma_f32 v44, v174, v43, v44
	v_fma_f32 v12, -v173, v59, v12
	v_fma_f32 v28, -v175, v43, v28
	v_fma_f32 v60, v173, v11, v60
	v_fma_f32 v44, v175, v27, v44
	v_fma_f32 v13, v172, v12, v13
	v_fma_f32 v29, v174, v28, v29
	v_fma_f32 v61, v172, v60, v61
	v_fma_f32 v45, v174, v44, v45
	v_fma_f32 v13, -v173, v60, v13
	v_fma_f32 v29, -v175, v44, v29
	v_fma_f32 v61, v173, v12, v61
	v_fma_f32 v45, v175, v28, v45
	v_fma_f32 v14, v172, v13, v14
	v_fma_f32 v30, v174, v29, v30
	v_fma_f32 v62, v172, v61, v62
	v_fma_f32 v46, v174, v45, v46
	v_fma_f32 v14, -v173, v61, v14
	v_fma_f32 v30, -v175, v45, v30
	v_fma_f32 v62, v173, v13, v62
	v_fma_f32 v46, v175, v29, v46
	v_fma_f32 v15, v172, v14, v15
	v_fma_f32 v31, v174, v30, v31
	v_fma_f32 v63, v172, v62, v63
	v_fma_f32 v47, v174, v46, v47
	v_fma_f32 v15, -v173, v62, v15
	v_fma_f32 v31, -v175, v46, v31
	v_fma_f32 v63, v173, v14, v63
	v_fma_f32 v47, v175, v30, v47
	v_mov_b32_e32 v186, v15
	v_mov_b32_e32 v187, v63
	v_mov_b32_e32 v188, v31
	v_mov_b32_e32 v189, v47
	v_cvt_pk_bf16_f32 v190, v12, v13
	v_cvt_pk_bf16_f32 v191, v14, v15
	v_cvt_pk_bf16_f32 v192, v28, v29
	v_cvt_pk_bf16_f32 v193, v30, v31
	ds_write2st64_b64 v210, v[190:191], v[192:193] offset1:4
	v_cvt_pk_bf16_f32 v212, v60, v61
	v_cvt_pk_bf16_f32 v213, v62, v63
	v_cvt_pk_bf16_f32 v214, v44, v45
	v_cvt_pk_bf16_f32 v215, v46, v47
	ds_write2st64_b64 v210, v[212:213], v[214:215] offset0:8 offset1:12
	s_waitcnt lgkmcnt(0)
	ds_read_b64_tr_b16 v[0:1], v151 offset:0
	ds_read_b64_tr_b16 v[2:3], v199 offset:0
	ds_read_b64_tr_b16 v[28:29], v151 offset:1024
	ds_read_b64_tr_b16 v[30:31], v199 offset:1024
	ds_read_b64_tr_b16 v[24:25], v151 offset:2048
	ds_read_b64_tr_b16 v[26:27], v199 offset:2048
	ds_read_b64_tr_b16 v[20:21], v151 offset:3072
	ds_read_b64_tr_b16 v[22:23], v199 offset:3072
	ds_read_b64_tr_b16 v[16:17], v151 offset:4096
	ds_read_b64_tr_b16 v[18:19], v199 offset:4096
	ds_read_b64_tr_b16 v[44:45], v151 offset:5120
	ds_read_b64_tr_b16 v[46:47], v199 offset:5120
	ds_read_b64_tr_b16 v[40:41], v151 offset:6144
	ds_read_b64_tr_b16 v[42:43], v199 offset:6144
	ds_read_b64_tr_b16 v[52:53], v151 offset:7168
	ds_read_b64_tr_b16 v[54:55], v199 offset:7168
	s_waitcnt lgkmcnt(0)
	s_nop 0
	v_mfma_f32_32x32x16_bf16 v[0:15], v[68:71], v[0:3], 0
	v_mfma_f32_32x32x16_bf16 v[0:15], v[64:67], v[28:31], v[0:15]
	v_mfma_f32_32x32x16_bf16 v[0:15], v[76:79], v[24:27], v[0:15]
	v_mfma_f32_32x32x16_bf16 v[0:15], v[72:75], v[20:23], v[0:15]
	v_mfma_f32_32x32x16_bf16 v[0:15], v[84:87], v[16:19], v[0:15]
	v_mfma_f32_32x32x16_bf16 v[0:15], v[80:83], v[44:47], v[0:15]
	v_mfma_f32_32x32x16_bf16 v[0:15], v[92:95], v[40:43], v[0:15]
	v_mfma_f32_32x32x16_bf16 v[0:15], v[88:91], v[52:55], v[0:15]
	s_and_saveexec_b64 s[2:3], s[14:15]
	s_cbranch_execz .LBB0_190
	s_nop 7
	v_add_u32_e32 v16, v200, v146
	v_add_u32_e32 v16, 0x2000, v16
	ds_read2_b64 v[16:19], v16 offset1:2
	s_waitcnt lgkmcnt(0)
	v_lshlrev_b32_e32 v10, 16, v19
	v_and_b32_e32 v11, 0xffff0000, v19
	v_pk_fma_f32 v[6:7], v[102:103], v[10:11], v[6:7]
	s_nop 0
	v_mul_f32_e32 v10, v7, v7
	v_fmaak_f32 v10, v240, v10, 0xc0135761
	v_mul_f32_e32 v11, v6, v6
	v_mul_f32_e32 v10, v7, v10
	v_fmaak_f32 v11, v240, v11, 0xc0135761
	v_mul_f32_e32 v11, v6, v11
	v_exp_f32_e32 v10, v10
	v_exp_f32_e32 v11, v11
	v_add_f32_e32 v8, 1.0, v10
	v_rcp_f32_e32 v9, v8
	v_add_f32_e32 v8, 1.0, v11
	v_lshlrev_b32_e32 v10, 16, v18
	v_and_b32_e32 v11, 0xffff0000, v18
	v_pk_fma_f32 v[4:5], v[100:101], v[10:11], v[4:5]
	v_and_b32_e32 v13, 0xffff0000, v17
	v_mul_f32_e32 v10, v5, v5
	v_fmaak_f32 v10, v240, v10, 0xc0135761
	v_mul_f32_e32 v11, v4, v4
	v_mul_f32_e32 v10, v5, v10
	v_fmaak_f32 v11, v240, v11, 0xc0135761
	v_mul_f32_e32 v11, v4, v11
	v_exp_f32_e32 v10, v10
	v_exp_f32_e32 v12, v11
	v_and_b32_e32 v15, 0xffff0000, v16
	v_add_f32_e32 v10, 1.0, v10
	v_rcp_f32_e32 v11, v10
	v_add_f32_e32 v10, 1.0, v12
	v_lshlrev_b32_e32 v12, 16, v17
	v_pk_fma_f32 v[2:3], v[98:99], v[12:13], v[2:3]
	v_rcp_f32_e32 v8, v8
	v_mul_f32_e32 v12, v3, v3
	v_fmaak_f32 v12, v240, v12, 0xc0135761
	v_mul_f32_e32 v13, v2, v2
	v_mul_f32_e32 v12, v3, v12
	v_fmaak_f32 v13, v240, v13, 0xc0135761
	v_mul_f32_e32 v13, v2, v13
	v_exp_f32_e32 v12, v12
	v_exp_f32_e32 v14, v13
	v_rcp_f32_e32 v10, v10
	v_add_f32_e32 v12, 1.0, v12
	v_rcp_f32_e32 v13, v12
	v_add_f32_e32 v12, 1.0, v14
	v_lshlrev_b32_e32 v14, 16, v16
	v_pk_fma_f32 v[0:1], v[96:97], v[14:15], v[0:1]
	v_rcp_f32_e32 v12, v12
	v_mul_f32_e32 v14, v1, v1
	v_fmaak_f32 v14, v240, v14, 0xc0135761
	v_mul_f32_e32 v15, v0, v0
	v_mul_f32_e32 v14, v1, v14
	v_fmaak_f32 v15, v240, v15, 0xc0135761
	v_mul_f32_e32 v15, v0, v15
	v_exp_f32_e32 v14, v14
	v_exp_f32_e32 v16, v15
	s_cmp_eq_u32 s24, 0
	v_add_f32_e32 v14, 1.0, v14
	v_rcp_f32_e32 v15, v14
	v_add_f32_e32 v14, 1.0, v16
	v_rcp_f32_e32 v14, v14
	s_cselect_b64 vcc, -1, 0
	v_pk_mul_f32 v[6:7], v[6:7], v[8:9]
	v_cndmask_b32_e64 v9, v123, 0, vcc
	v_cndmask_b32_e32 v8, v122, v154, vcc
	v_pk_mul_f32 v[2:3], v[2:3], v[12:13]
	v_pk_mul_f32 v[0:1], v[0:1], v[14:15]
	v_lshlrev_b64 v[8:9], 11, v[8:9]
	v_pk_mul_f32 v[4:5], v[4:5], v[10:11]
	v_lshl_add_u64 v[8:9], v[126:127], 0, v[8:9]
	v_cvt_pk_bf16_f32 v0, v0, v1
	v_cvt_pk_bf16_f32 v1, v2, v3
	v_cvt_pk_bf16_f32 v2, v4, v5
	v_cvt_pk_bf16_f32 v3, v6, v7
	global_store_dwordx2 v[8:9], v[0:1], off
	global_store_dwordx2 v[8:9], v[2:3], off offset:16
.LBB0_190:
	s_or_b64 exec, exec, s[2:3]
	s_add_i32 s67, s24, 4
	s_min_i32 s2, s67, s23
	s_nop 0
	v_sub_co_u32_e64 v0, vcc, s2, 1
	v_ashrrev_i32_e32 v1, 31, v0
	v_lshl_add_u64 v[0:1], v[0:1], 4, v[120:121]
	v_cndmask_b32_e64 v1, v1, 0, vcc
	v_cndmask_b32_e32 v0, v0, v154, vcc
	v_lshlrev_b64 v[0:1], 11, v[0:1]
	v_lshl_add_u64 v[0:1], v[184:185], 0, v[0:1]
	global_load_dwordx4 v[108:111], v[0:1], off
	s_add_i32 s52, s24, 1
	s_cmp_ge_i32 s52, s22
	s_cbranch_scc1 .LBB0_195
	s_waitcnt vmcnt(9)
	v_mfma_f32_32x32x16_bf16 v[0:15], v[104:107], v[128:131], 0
	v_mfma_f32_32x32x16_bf16 v[16:31], v[104:107], v[132:135], 0
	v_mfma_f32_32x32x16_bf16 v[48:63], v[104:107], v[136:139], 0
	v_mfma_f32_32x32x16_bf16 v[32:47], v[104:107], v[140:143], 0
	ds_write_b128 v148, v[104:107] offset:8192
	s_cmp_gt_i32 s24, -1
	s_cselect_b64 s[2:3], -1, 0
	s_or_b64 s[14:15], s[2:3], s[50:51]
	s_nop 7
	v_fma_f32 v0, v172, v186, v0
	v_fma_f32 v16, v174, v188, v16
	v_fma_f32 v48, v172, v187, v48
	v_fma_f32 v32, v174, v189, v32
	v_fma_f32 v0, -v173, v187, v0
	v_fma_f32 v16, -v175, v189, v16
	v_fma_f32 v48, v173, v186, v48
	v_fma_f32 v32, v175, v188, v32
	v_fma_f32 v1, v172, v0, v1
	v_fma_f32 v17, v174, v16, v17
	v_fma_f32 v49, v172, v48, v49
	v_fma_f32 v33, v174, v32, v33
	v_fma_f32 v1, -v173, v48, v1
	v_fma_f32 v17, -v175, v32, v17
	v_fma_f32 v49, v173, v0, v49
	v_fma_f32 v33, v175, v16, v33
	v_fma_f32 v2, v172, v1, v2
	v_fma_f32 v18, v174, v17, v18
	v_fma_f32 v50, v172, v49, v50
	v_fma_f32 v34, v174, v33, v34
	v_fma_f32 v2, -v173, v49, v2
	v_fma_f32 v18, -v175, v33, v18
	v_fma_f32 v50, v173, v1, v50
	v_fma_f32 v34, v175, v17, v34
	v_fma_f32 v3, v172, v2, v3
	v_fma_f32 v19, v174, v18, v19
	v_fma_f32 v51, v172, v50, v51
	v_fma_f32 v35, v174, v34, v35
	v_fma_f32 v3, -v173, v50, v3
	v_fma_f32 v19, -v175, v34, v19
	v_fma_f32 v51, v173, v2, v51
	v_fma_f32 v35, v175, v18, v35
	v_cvt_pk_bf16_f32 v190, v0, v1
	v_cvt_pk_bf16_f32 v191, v2, v3
	v_cvt_pk_bf16_f32 v192, v16, v17
	v_cvt_pk_bf16_f32 v193, v18, v19
	ds_write2st64_b64 v207, v[190:191], v[192:193] offset1:4
	v_cvt_pk_bf16_f32 v212, v48, v49
	v_cvt_pk_bf16_f32 v213, v50, v51
	v_cvt_pk_bf16_f32 v214, v32, v33
	v_cvt_pk_bf16_f32 v215, v34, v35
	ds_write2st64_b64 v207, v[212:213], v[214:215] offset0:8 offset1:12
	v_fma_f32 v4, v172, v3, v4
	v_fma_f32 v20, v174, v19, v20
	v_fma_f32 v52, v172, v51, v52
	v_fma_f32 v36, v174, v35, v36
	v_fma_f32 v4, -v173, v51, v4
	v_fma_f32 v20, -v175, v35, v20
	v_fma_f32 v52, v173, v3, v52
	v_fma_f32 v36, v175, v19, v36
	v_fma_f32 v5, v172, v4, v5
	v_fma_f32 v21, v174, v20, v21
	v_fma_f32 v53, v172, v52, v53
	v_fma_f32 v37, v174, v36, v37
	v_fma_f32 v5, -v173, v52, v5
	v_fma_f32 v21, -v175, v36, v21
	v_fma_f32 v53, v173, v4, v53
	v_fma_f32 v37, v175, v20, v37
	v_fma_f32 v6, v172, v5, v6
	v_fma_f32 v22, v174, v21, v22
	v_fma_f32 v54, v172, v53, v54
	v_fma_f32 v38, v174, v37, v38
	v_fma_f32 v6, -v173, v53, v6
	v_fma_f32 v22, -v175, v37, v22
	v_fma_f32 v54, v173, v5, v54
	v_fma_f32 v38, v175, v21, v38
	v_fma_f32 v7, v172, v6, v7
	v_fma_f32 v23, v174, v22, v23
	v_fma_f32 v55, v172, v54, v55
	v_fma_f32 v39, v174, v38, v39
	v_fma_f32 v7, -v173, v54, v7
	v_fma_f32 v23, -v175, v38, v23
	v_fma_f32 v55, v173, v6, v55
	v_fma_f32 v39, v175, v22, v39
	v_cvt_pk_bf16_f32 v190, v4, v5
	v_cvt_pk_bf16_f32 v191, v6, v7
	v_cvt_pk_bf16_f32 v192, v20, v21
	v_cvt_pk_bf16_f32 v193, v22, v23
	ds_write2st64_b64 v208, v[190:191], v[192:193] offset1:4
	v_cvt_pk_bf16_f32 v212, v52, v53
	v_cvt_pk_bf16_f32 v213, v54, v55
	v_cvt_pk_bf16_f32 v214, v36, v37
	v_cvt_pk_bf16_f32 v215, v38, v39
	ds_write2st64_b64 v208, v[212:213], v[214:215] offset0:8 offset1:12
	v_fma_f32 v8, v172, v7, v8
	v_fma_f32 v24, v174, v23, v24
	v_fma_f32 v56, v172, v55, v56
	v_fma_f32 v40, v174, v39, v40
	v_fma_f32 v8, -v173, v55, v8
	v_fma_f32 v24, -v175, v39, v24
	v_fma_f32 v56, v173, v7, v56
	v_fma_f32 v40, v175, v23, v40
	v_fma_f32 v9, v172, v8, v9
	v_fma_f32 v25, v174, v24, v25
	v_fma_f32 v57, v172, v56, v57
	v_fma_f32 v41, v174, v40, v41
	v_fma_f32 v9, -v173, v56, v9
	v_fma_f32 v25, -v175, v40, v25
	v_fma_f32 v57, v173, v8, v57
	v_fma_f32 v41, v175, v24, v41
	v_fma_f32 v10, v172, v9, v10
	v_fma_f32 v26, v174, v25, v26
	v_fma_f32 v58, v172, v57, v58
	v_fma_f32 v42, v174, v41, v42
	v_fma_f32 v10, -v173, v57, v10
	v_fma_f32 v26, -v175, v41, v26
	v_fma_f32 v58, v173, v9, v58
	v_fma_f32 v42, v175, v25, v42
	v_fma_f32 v11, v172, v10, v11
	v_fma_f32 v27, v174, v26, v27
	v_fma_f32 v59, v172, v58, v59
	v_fma_f32 v43, v174, v42, v43
	v_fma_f32 v11, -v173, v58, v11
	v_fma_f32 v27, -v175, v42, v27
	v_fma_f32 v59, v173, v10, v59
	v_fma_f32 v43, v175, v26, v43
	v_cvt_pk_bf16_f32 v190, v8, v9
	v_cvt_pk_bf16_f32 v191, v10, v11
	v_cvt_pk_bf16_f32 v192, v24, v25
	v_cvt_pk_bf16_f32 v193, v26, v27
	ds_write2st64_b64 v209, v[190:191], v[192:193] offset1:4
	v_cvt_pk_bf16_f32 v212, v56, v57
	v_cvt_pk_bf16_f32 v213, v58, v59
	v_cvt_pk_bf16_f32 v214, v40, v41
	v_cvt_pk_bf16_f32 v215, v42, v43
	ds_write2st64_b64 v209, v[212:213], v[214:215] offset0:8 offset1:12
	v_fma_f32 v12, v172, v11, v12
	v_fma_f32 v28, v174, v27, v28
	v_fma_f32 v60, v172, v59, v60
	v_fma_f32 v44, v174, v43, v44
	v_fma_f32 v12, -v173, v59, v12
	v_fma_f32 v28, -v175, v43, v28
	v_fma_f32 v60, v173, v11, v60
	v_fma_f32 v44, v175, v27, v44
	v_fma_f32 v13, v172, v12, v13
	v_fma_f32 v29, v174, v28, v29
	v_fma_f32 v61, v172, v60, v61
	v_fma_f32 v45, v174, v44, v45
	v_fma_f32 v13, -v173, v60, v13
	v_fma_f32 v29, -v175, v44, v29
	v_fma_f32 v61, v173, v12, v61
	v_fma_f32 v45, v175, v28, v45
	v_fma_f32 v14, v172, v13, v14
	v_fma_f32 v30, v174, v29, v30
	v_fma_f32 v62, v172, v61, v62
	v_fma_f32 v46, v174, v45, v46
	v_fma_f32 v14, -v173, v61, v14
	v_fma_f32 v30, -v175, v45, v30
	v_fma_f32 v62, v173, v13, v62
	v_fma_f32 v46, v175, v29, v46
	v_fma_f32 v15, v172, v14, v15
	v_fma_f32 v31, v174, v30, v31
	v_fma_f32 v63, v172, v62, v63
	v_fma_f32 v47, v174, v46, v47
	v_fma_f32 v15, -v173, v62, v15
	v_fma_f32 v31, -v175, v46, v31
	v_fma_f32 v63, v173, v14, v63
	v_fma_f32 v47, v175, v30, v47
	v_mov_b32_e32 v186, v15
	v_mov_b32_e32 v187, v63
	v_mov_b32_e32 v188, v31
	v_mov_b32_e32 v189, v47
	v_cvt_pk_bf16_f32 v190, v12, v13
	v_cvt_pk_bf16_f32 v191, v14, v15
	v_cvt_pk_bf16_f32 v192, v28, v29
	v_cvt_pk_bf16_f32 v193, v30, v31
	ds_write2st64_b64 v210, v[190:191], v[192:193] offset1:4
	v_cvt_pk_bf16_f32 v212, v60, v61
	v_cvt_pk_bf16_f32 v213, v62, v63
	v_cvt_pk_bf16_f32 v214, v44, v45
	v_cvt_pk_bf16_f32 v215, v46, v47
	ds_write2st64_b64 v210, v[212:213], v[214:215] offset0:8 offset1:12
	s_waitcnt lgkmcnt(0)
	ds_read_b64_tr_b16 v[0:1], v151 offset:0
	ds_read_b64_tr_b16 v[2:3], v199 offset:0
	ds_read_b64_tr_b16 v[28:29], v151 offset:1024
	ds_read_b64_tr_b16 v[30:31], v199 offset:1024
	ds_read_b64_tr_b16 v[24:25], v151 offset:2048
	ds_read_b64_tr_b16 v[26:27], v199 offset:2048
	ds_read_b64_tr_b16 v[20:21], v151 offset:3072
	ds_read_b64_tr_b16 v[22:23], v199 offset:3072
	ds_read_b64_tr_b16 v[16:17], v151 offset:4096
	ds_read_b64_tr_b16 v[18:19], v199 offset:4096
	ds_read_b64_tr_b16 v[44:45], v151 offset:5120
	ds_read_b64_tr_b16 v[46:47], v199 offset:5120
	ds_read_b64_tr_b16 v[40:41], v151 offset:6144
	ds_read_b64_tr_b16 v[42:43], v199 offset:6144
	ds_read_b64_tr_b16 v[52:53], v151 offset:7168
	ds_read_b64_tr_b16 v[54:55], v199 offset:7168
	s_waitcnt lgkmcnt(0)
	s_nop 0
	v_mfma_f32_32x32x16_bf16 v[0:15], v[68:71], v[0:3], 0
	v_mfma_f32_32x32x16_bf16 v[0:15], v[64:67], v[28:31], v[0:15]
	v_mfma_f32_32x32x16_bf16 v[0:15], v[76:79], v[24:27], v[0:15]
	v_mfma_f32_32x32x16_bf16 v[0:15], v[72:75], v[20:23], v[0:15]
	v_mfma_f32_32x32x16_bf16 v[0:15], v[84:87], v[16:19], v[0:15]
	v_mfma_f32_32x32x16_bf16 v[0:15], v[80:83], v[44:47], v[0:15]
	v_mfma_f32_32x32x16_bf16 v[0:15], v[92:95], v[40:43], v[0:15]
	v_mfma_f32_32x32x16_bf16 v[0:15], v[88:91], v[52:55], v[0:15]
	s_and_saveexec_b64 s[2:3], s[14:15]
	s_cbranch_execz .LBB0_193
	s_nop 7
	v_add_u32_e32 v16, v200, v146
	v_add_u32_e32 v16, 0x2000, v16
	ds_read2_b64 v[16:19], v16 offset1:2
	s_waitcnt lgkmcnt(0)
	v_lshlrev_b32_e32 v10, 16, v19
	v_and_b32_e32 v11, 0xffff0000, v19
	v_pk_fma_f32 v[6:7], v[102:103], v[10:11], v[6:7]
	s_nop 0
	v_mul_f32_e32 v10, v7, v7
	v_fmaak_f32 v10, v240, v10, 0xc0135761
	v_mul_f32_e32 v11, v6, v6
	v_mul_f32_e32 v10, v7, v10
	v_fmaak_f32 v11, v240, v11, 0xc0135761
	v_mul_f32_e32 v11, v6, v11
	v_exp_f32_e32 v10, v10
	v_exp_f32_e32 v11, v11
	v_add_f32_e32 v8, 1.0, v10
	v_rcp_f32_e32 v9, v8
	v_add_f32_e32 v8, 1.0, v11
	v_lshlrev_b32_e32 v10, 16, v18
	v_and_b32_e32 v11, 0xffff0000, v18
	v_pk_fma_f32 v[4:5], v[100:101], v[10:11], v[4:5]
	v_and_b32_e32 v13, 0xffff0000, v17
	v_mul_f32_e32 v10, v5, v5
	v_fmaak_f32 v10, v240, v10, 0xc0135761
	v_mul_f32_e32 v11, v4, v4
	v_mul_f32_e32 v10, v5, v10
	v_fmaak_f32 v11, v240, v11, 0xc0135761
	v_mul_f32_e32 v11, v4, v11
	v_exp_f32_e32 v10, v10
	v_exp_f32_e32 v12, v11
	v_and_b32_e32 v15, 0xffff0000, v16
	v_add_f32_e32 v10, 1.0, v10
	v_rcp_f32_e32 v11, v10
	v_add_f32_e32 v10, 1.0, v12
	v_lshlrev_b32_e32 v12, 16, v17
	v_pk_fma_f32 v[2:3], v[98:99], v[12:13], v[2:3]
	v_rcp_f32_e32 v8, v8
	v_mul_f32_e32 v12, v3, v3
	v_fmaak_f32 v12, v240, v12, 0xc0135761
	v_mul_f32_e32 v13, v2, v2
	v_mul_f32_e32 v12, v3, v12
	v_fmaak_f32 v13, v240, v13, 0xc0135761
	v_mul_f32_e32 v13, v2, v13
	v_exp_f32_e32 v12, v12
	v_exp_f32_e32 v14, v13
	v_rcp_f32_e32 v10, v10
	v_add_f32_e32 v12, 1.0, v12
	v_rcp_f32_e32 v13, v12
	v_add_f32_e32 v12, 1.0, v14
	v_lshlrev_b32_e32 v14, 16, v16
	v_pk_fma_f32 v[0:1], v[96:97], v[14:15], v[0:1]
	v_rcp_f32_e32 v12, v12
	v_mul_f32_e32 v14, v1, v1
	v_fmaak_f32 v14, v240, v14, 0xc0135761
	v_mul_f32_e32 v15, v0, v0
	v_mul_f32_e32 v14, v1, v14
	v_fmaak_f32 v15, v240, v15, 0xc0135761
	v_mul_f32_e32 v15, v0, v15
	v_exp_f32_e32 v14, v14
	v_exp_f32_e32 v16, v15
	s_cmp_eq_u32 s24, -1
	v_add_f32_e32 v14, 1.0, v14
	v_rcp_f32_e32 v15, v14
	v_add_f32_e32 v14, 1.0, v16
	v_rcp_f32_e32 v14, v14
	s_cselect_b64 vcc, -1, 0
	v_pk_mul_f32 v[6:7], v[6:7], v[8:9]
	v_cndmask_b32_e64 v9, v125, 0, vcc
	v_cndmask_b32_e32 v8, v124, v154, vcc
	v_pk_mul_f32 v[2:3], v[2:3], v[12:13]
	v_pk_mul_f32 v[0:1], v[0:1], v[14:15]
	v_lshlrev_b64 v[8:9], 11, v[8:9]
	v_pk_mul_f32 v[4:5], v[4:5], v[10:11]
	v_lshl_add_u64 v[8:9], v[126:127], 0, v[8:9]
	v_cvt_pk_bf16_f32 v0, v0, v1
	v_cvt_pk_bf16_f32 v1, v2, v3
	v_cvt_pk_bf16_f32 v2, v4, v5
	v_cvt_pk_bf16_f32 v3, v6, v7
	global_store_dwordx2 v[8:9], v[0:1], off
	global_store_dwordx2 v[8:9], v[2:3], off offset:16

.LBB0_196:
	s_waitcnt vmcnt(9)
	v_mfma_f32_32x32x16_bf16 v[0:15], v[116:119], v[128:131], 0
	v_mfma_f32_32x32x16_bf16 v[16:31], v[116:119], v[132:135], 0
	v_mfma_f32_32x32x16_bf16 v[48:63], v[116:119], v[136:139], 0
	v_mfma_f32_32x32x16_bf16 v[32:47], v[116:119], v[140:143], 0
	ds_write_b128 v148, v[116:119] offset:8192
	s_cmp_gt_i32 s24, -2
	s_cselect_b64 s[2:3], -1, 0
	s_or_b64 s[68:69], s[2:3], s[50:51]
	s_nop 7
	v_fma_f32 v0, v172, v186, v0
	v_fma_f32 v16, v174, v188, v16
	v_fma_f32 v48, v172, v187, v48
	v_fma_f32 v32, v174, v189, v32
	v_fma_f32 v0, -v173, v187, v0
	v_fma_f32 v16, -v175, v189, v16
	v_fma_f32 v48, v173, v186, v48
	v_fma_f32 v32, v175, v188, v32
	v_fma_f32 v1, v172, v0, v1
	v_fma_f32 v17, v174, v16, v17
	v_fma_f32 v49, v172, v48, v49
	v_fma_f32 v33, v174, v32, v33
	v_fma_f32 v1, -v173, v48, v1
	v_fma_f32 v17, -v175, v32, v17
	v_fma_f32 v49, v173, v0, v49
	v_fma_f32 v33, v175, v16, v33
	v_fma_f32 v2, v172, v1, v2
	v_fma_f32 v18, v174, v17, v18
	v_fma_f32 v50, v172, v49, v50
	v_fma_f32 v34, v174, v33, v34
	v_fma_f32 v2, -v173, v49, v2
	v_fma_f32 v18, -v175, v33, v18
	v_fma_f32 v50, v173, v1, v50
	v_fma_f32 v34, v175, v17, v34
	v_fma_f32 v3, v172, v2, v3
	v_fma_f32 v19, v174, v18, v19
	v_fma_f32 v51, v172, v50, v51
	v_fma_f32 v35, v174, v34, v35
	v_fma_f32 v3, -v173, v50, v3
	v_fma_f32 v19, -v175, v34, v19
	v_fma_f32 v51, v173, v2, v51
	v_fma_f32 v35, v175, v18, v35
	v_cvt_pk_bf16_f32 v190, v0, v1
	v_cvt_pk_bf16_f32 v191, v2, v3
	v_cvt_pk_bf16_f32 v192, v16, v17
	v_cvt_pk_bf16_f32 v193, v18, v19
	ds_write2st64_b64 v207, v[190:191], v[192:193] offset1:4
	v_cvt_pk_bf16_f32 v212, v48, v49
	v_cvt_pk_bf16_f32 v213, v50, v51
	v_cvt_pk_bf16_f32 v214, v32, v33
	v_cvt_pk_bf16_f32 v215, v34, v35
	ds_write2st64_b64 v207, v[212:213], v[214:215] offset0:8 offset1:12
	v_fma_f32 v4, v172, v3, v4
	v_fma_f32 v20, v174, v19, v20
	v_fma_f32 v52, v172, v51, v52
	v_fma_f32 v36, v174, v35, v36
	v_fma_f32 v4, -v173, v51, v4
	v_fma_f32 v20, -v175, v35, v20
	v_fma_f32 v52, v173, v3, v52
	v_fma_f32 v36, v175, v19, v36
	v_fma_f32 v5, v172, v4, v5
	v_fma_f32 v21, v174, v20, v21
	v_fma_f32 v53, v172, v52, v53
	v_fma_f32 v37, v174, v36, v37
	v_fma_f32 v5, -v173, v52, v5
	v_fma_f32 v21, -v175, v36, v21
	v_fma_f32 v53, v173, v4, v53
	v_fma_f32 v37, v175, v20, v37
	v_fma_f32 v6, v172, v5, v6
	v_fma_f32 v22, v174, v21, v22
	v_fma_f32 v54, v172, v53, v54
	v_fma_f32 v38, v174, v37, v38
	v_fma_f32 v6, -v173, v53, v6
	v_fma_f32 v22, -v175, v37, v22
	v_fma_f32 v54, v173, v5, v54
	v_fma_f32 v38, v175, v21, v38
	v_fma_f32 v7, v172, v6, v7
	v_fma_f32 v23, v174, v22, v23
	v_fma_f32 v55, v172, v54, v55
	v_fma_f32 v39, v174, v38, v39
	v_fma_f32 v7, -v173, v54, v7
	v_fma_f32 v23, -v175, v38, v23
	v_fma_f32 v55, v173, v6, v55
	v_fma_f32 v39, v175, v22, v39
	v_cvt_pk_bf16_f32 v190, v4, v5
	v_cvt_pk_bf16_f32 v191, v6, v7
	v_cvt_pk_bf16_f32 v192, v20, v21
	v_cvt_pk_bf16_f32 v193, v22, v23
	ds_write2st64_b64 v208, v[190:191], v[192:193] offset1:4
	v_cvt_pk_bf16_f32 v212, v52, v53
	v_cvt_pk_bf16_f32 v213, v54, v55
	v_cvt_pk_bf16_f32 v214, v36, v37
	v_cvt_pk_bf16_f32 v215, v38, v39
	ds_write2st64_b64 v208, v[212:213], v[214:215] offset0:8 offset1:12
	v_fma_f32 v8, v172, v7, v8
	v_fma_f32 v24, v174, v23, v24
	v_fma_f32 v56, v172, v55, v56
	v_fma_f32 v40, v174, v39, v40
	v_fma_f32 v8, -v173, v55, v8
	v_fma_f32 v24, -v175, v39, v24
	v_fma_f32 v56, v173, v7, v56
	v_fma_f32 v40, v175, v23, v40
	v_fma_f32 v9, v172, v8, v9
	v_fma_f32 v25, v174, v24, v25
	v_fma_f32 v57, v172, v56, v57
	v_fma_f32 v41, v174, v40, v41
	v_fma_f32 v9, -v173, v56, v9
	v_fma_f32 v25, -v175, v40, v25
	v_fma_f32 v57, v173, v8, v57
	v_fma_f32 v41, v175, v24, v41
	v_fma_f32 v10, v172, v9, v10
	v_fma_f32 v26, v174, v25, v26
	v_fma_f32 v58, v172, v57, v58
	v_fma_f32 v42, v174, v41, v42
	v_fma_f32 v10, -v173, v57, v10
	v_fma_f32 v26, -v175, v41, v26
	v_fma_f32 v58, v173, v9, v58
	v_fma_f32 v42, v175, v25, v42
	v_fma_f32 v11, v172, v10, v11
	v_fma_f32 v27, v174, v26, v27
	v_fma_f32 v59, v172, v58, v59
	v_fma_f32 v43, v174, v42, v43
	v_fma_f32 v11, -v173, v58, v11
	v_fma_f32 v27, -v175, v42, v27
	v_fma_f32 v59, v173, v10, v59
	v_fma_f32 v43, v175, v26, v43
	v_cvt_pk_bf16_f32 v190, v8, v9
	v_cvt_pk_bf16_f32 v191, v10, v11
	v_cvt_pk_bf16_f32 v192, v24, v25
	v_cvt_pk_bf16_f32 v193, v26, v27
	ds_write2st64_b64 v209, v[190:191], v[192:193] offset1:4
	v_cvt_pk_bf16_f32 v212, v56, v57
	v_cvt_pk_bf16_f32 v213, v58, v59
	v_cvt_pk_bf16_f32 v214, v40, v41
	v_cvt_pk_bf16_f32 v215, v42, v43
	ds_write2st64_b64 v209, v[212:213], v[214:215] offset0:8 offset1:12
	v_fma_f32 v12, v172, v11, v12
	v_fma_f32 v28, v174, v27, v28
	v_fma_f32 v60, v172, v59, v60
	v_fma_f32 v44, v174, v43, v44
	v_fma_f32 v12, -v173, v59, v12
	v_fma_f32 v28, -v175, v43, v28
	v_fma_f32 v60, v173, v11, v60
	v_fma_f32 v44, v175, v27, v44
	v_fma_f32 v13, v172, v12, v13
	v_fma_f32 v29, v174, v28, v29
	v_fma_f32 v61, v172, v60, v61
	v_fma_f32 v45, v174, v44, v45
	v_fma_f32 v13, -v173, v60, v13
	v_fma_f32 v29, -v175, v44, v29
	v_fma_f32 v61, v173, v12, v61
	v_fma_f32 v45, v175, v28, v45
	v_fma_f32 v14, v172, v13, v14
	v_fma_f32 v30, v174, v29, v30
	v_fma_f32 v62, v172, v61, v62
	v_fma_f32 v46, v174, v45, v46
	v_fma_f32 v14, -v173, v61, v14
	v_fma_f32 v30, -v175, v45, v30
	v_fma_f32 v62, v173, v13, v62
	v_fma_f32 v46, v175, v29, v46
	v_fma_f32 v15, v172, v14, v15
	v_fma_f32 v31, v174, v30, v31
	v_fma_f32 v63, v172, v62, v63
	v_fma_f32 v47, v174, v46, v47
	v_fma_f32 v15, -v173, v62, v15
	v_fma_f32 v31, -v175, v46, v31
	v_fma_f32 v63, v173, v14, v63
	v_fma_f32 v47, v175, v30, v47
	v_mov_b32_e32 v186, v15
	v_mov_b32_e32 v187, v63
	v_mov_b32_e32 v188, v31
	v_mov_b32_e32 v189, v47
	v_cvt_pk_bf16_f32 v190, v12, v13
	v_cvt_pk_bf16_f32 v191, v14, v15
	v_cvt_pk_bf16_f32 v192, v28, v29
	v_cvt_pk_bf16_f32 v193, v30, v31
	ds_write2st64_b64 v210, v[190:191], v[192:193] offset1:4
	v_cvt_pk_bf16_f32 v212, v60, v61
	v_cvt_pk_bf16_f32 v213, v62, v63
	v_cvt_pk_bf16_f32 v214, v44, v45
	v_cvt_pk_bf16_f32 v215, v46, v47
	ds_write2st64_b64 v210, v[212:213], v[214:215] offset0:8 offset1:12
	s_waitcnt lgkmcnt(0)
	ds_read_b64_tr_b16 v[0:1], v151 offset:0
	ds_read_b64_tr_b16 v[2:3], v199 offset:0
	ds_read_b64_tr_b16 v[28:29], v151 offset:1024
	ds_read_b64_tr_b16 v[30:31], v199 offset:1024
	ds_read_b64_tr_b16 v[24:25], v151 offset:2048
	ds_read_b64_tr_b16 v[26:27], v199 offset:2048
	ds_read_b64_tr_b16 v[20:21], v151 offset:3072
	ds_read_b64_tr_b16 v[22:23], v199 offset:3072
	ds_read_b64_tr_b16 v[16:17], v151 offset:4096
	ds_read_b64_tr_b16 v[18:19], v199 offset:4096
	ds_read_b64_tr_b16 v[44:45], v151 offset:5120
	ds_read_b64_tr_b16 v[46:47], v199 offset:5120
	ds_read_b64_tr_b16 v[40:41], v151 offset:6144
	ds_read_b64_tr_b16 v[42:43], v199 offset:6144
	ds_read_b64_tr_b16 v[52:53], v151 offset:7168
	ds_read_b64_tr_b16 v[54:55], v199 offset:7168
	s_waitcnt lgkmcnt(0)
	s_nop 0
	v_mfma_f32_32x32x16_bf16 v[0:15], v[68:71], v[0:3], 0
	v_mfma_f32_32x32x16_bf16 v[0:15], v[64:67], v[28:31], v[0:15]
	v_mfma_f32_32x32x16_bf16 v[0:15], v[76:79], v[24:27], v[0:15]
	v_mfma_f32_32x32x16_bf16 v[0:15], v[72:75], v[20:23], v[0:15]
	v_mfma_f32_32x32x16_bf16 v[0:15], v[84:87], v[16:19], v[0:15]
	v_mfma_f32_32x32x16_bf16 v[0:15], v[80:83], v[44:47], v[0:15]
	v_mfma_f32_32x32x16_bf16 v[0:15], v[92:95], v[40:43], v[0:15]
	v_mfma_f32_32x32x16_bf16 v[0:15], v[88:91], v[52:55], v[0:15]
	s_and_saveexec_b64 s[2:3], s[68:69]
	s_cbranch_execz .LBB0_198
	s_nop 7
	v_add_u32_e32 v16, v200, v146
	v_add_u32_e32 v16, 0x2000, v16
	ds_read2_b64 v[16:19], v16 offset1:2
	s_waitcnt lgkmcnt(0)
	v_lshlrev_b32_e32 v10, 16, v19
	v_and_b32_e32 v11, 0xffff0000, v19
	v_pk_fma_f32 v[6:7], v[102:103], v[10:11], v[6:7]
	s_nop 0
	v_mul_f32_e32 v10, v7, v7
	v_fmaak_f32 v10, v240, v10, 0xc0135761
	v_mul_f32_e32 v11, v6, v6
	v_mul_f32_e32 v10, v7, v10
	v_fmaak_f32 v11, v240, v11, 0xc0135761
	v_mul_f32_e32 v11, v6, v11
	v_exp_f32_e32 v10, v10
	v_exp_f32_e32 v11, v11
	v_add_f32_e32 v8, 1.0, v10
	v_rcp_f32_e32 v9, v8
	v_add_f32_e32 v8, 1.0, v11
	v_lshlrev_b32_e32 v10, 16, v18
	v_and_b32_e32 v11, 0xffff0000, v18
	v_pk_fma_f32 v[4:5], v[100:101], v[10:11], v[4:5]
	v_and_b32_e32 v13, 0xffff0000, v17
	v_mul_f32_e32 v10, v5, v5
	v_fmaak_f32 v10, v240, v10, 0xc0135761
	v_mul_f32_e32 v11, v4, v4
	v_mul_f32_e32 v10, v5, v10
	v_fmaak_f32 v11, v240, v11, 0xc0135761
	v_mul_f32_e32 v11, v4, v11
	v_exp_f32_e32 v10, v10
	v_exp_f32_e32 v12, v11
	v_and_b32_e32 v15, 0xffff0000, v16
	v_add_f32_e32 v10, 1.0, v10
	v_rcp_f32_e32 v11, v10
	v_add_f32_e32 v10, 1.0, v12
	v_lshlrev_b32_e32 v12, 16, v17
	v_pk_fma_f32 v[2:3], v[98:99], v[12:13], v[2:3]
	v_rcp_f32_e32 v8, v8
	v_mul_f32_e32 v12, v3, v3
	v_fmaak_f32 v12, v240, v12, 0xc0135761
	v_mul_f32_e32 v13, v2, v2
	v_mul_f32_e32 v12, v3, v12
	v_fmaak_f32 v13, v240, v13, 0xc0135761
	v_mul_f32_e32 v13, v2, v13
	v_exp_f32_e32 v12, v12
	v_exp_f32_e32 v14, v13
	s_cmp_eq_u32 s24, -2
	v_add_f32_e32 v12, 1.0, v12
	v_rcp_f32_e32 v13, v12
	v_add_f32_e32 v12, 1.0, v14
	v_lshlrev_b32_e32 v14, 16, v16
	v_pk_fma_f32 v[0:1], v[96:97], v[14:15], v[0:1]
	v_rcp_f32_e32 v12, v12
	v_mul_f32_e32 v14, v1, v1
	v_fmaak_f32 v14, v240, v14, 0xc0135761
	v_mul_f32_e32 v15, v0, v0
	v_mul_f32_e32 v14, v1, v14
	v_fmaak_f32 v15, v240, v15, 0xc0135761
	v_mul_f32_e32 v15, v0, v15
	v_exp_f32_e32 v14, v14
	v_exp_f32_e32 v16, v15
	v_rcp_f32_e32 v10, v10
	v_add_f32_e32 v14, 1.0, v14
	v_rcp_f32_e32 v15, v14
	v_add_f32_e32 v14, 1.0, v16
	v_rcp_f32_e32 v14, v14
	s_cselect_b64 vcc, -1, 0
	s_ashr_i32 s53, s52, 31
	v_pk_mul_f32 v[6:7], v[6:7], v[8:9]
	v_lshl_add_u64 v[8:9], s[52:53], 4, v[120:121]
	v_cndmask_b32_e64 v9, v9, 0, vcc
	v_cndmask_b32_e32 v8, v8, v154, vcc
	v_pk_mul_f32 v[2:3], v[2:3], v[12:13]
	v_pk_mul_f32 v[0:1], v[0:1], v[14:15]
	v_lshlrev_b64 v[8:9], 11, v[8:9]
	v_pk_mul_f32 v[4:5], v[4:5], v[10:11]
	v_lshl_add_u64 v[8:9], v[126:127], 0, v[8:9]
	v_cvt_pk_bf16_f32 v0, v0, v1
	v_cvt_pk_bf16_f32 v1, v2, v3
	v_cvt_pk_bf16_f32 v2, v4, v5
	v_cvt_pk_bf16_f32 v3, v6, v7
	global_store_dwordx2 v[8:9], v[0:1], off
	global_store_dwordx2 v[8:9], v[2:3], off offset:16

.LBB0_199:
	s_waitcnt vmcnt(9)
	v_mfma_f32_32x32x16_bf16 v[0:15], v[112:115], v[128:131], 0
	v_mfma_f32_32x32x16_bf16 v[16:31], v[112:115], v[132:135], 0
	v_mfma_f32_32x32x16_bf16 v[48:63], v[112:115], v[136:139], 0
	v_mfma_f32_32x32x16_bf16 v[32:47], v[112:115], v[140:143], 0
	ds_write_b128 v148, v[112:115] offset:8192
	s_cmp_gt_i32 s24, -3
	s_cselect_b64 s[2:3], -1, 0
	s_or_b64 s[52:53], s[2:3], s[50:51]
	s_nop 7
	v_fma_f32 v0, v172, v186, v0
	v_fma_f32 v16, v174, v188, v16
	v_fma_f32 v48, v172, v187, v48
	v_fma_f32 v32, v174, v189, v32
	v_fma_f32 v0, -v173, v187, v0
	v_fma_f32 v16, -v175, v189, v16
	v_fma_f32 v48, v173, v186, v48
	v_fma_f32 v32, v175, v188, v32
	v_fma_f32 v1, v172, v0, v1
	v_fma_f32 v17, v174, v16, v17
	v_fma_f32 v49, v172, v48, v49
	v_fma_f32 v33, v174, v32, v33
	v_fma_f32 v1, -v173, v48, v1
	v_fma_f32 v17, -v175, v32, v17
	v_fma_f32 v49, v173, v0, v49
	v_fma_f32 v33, v175, v16, v33
	v_fma_f32 v2, v172, v1, v2
	v_fma_f32 v18, v174, v17, v18
	v_fma_f32 v50, v172, v49, v50
	v_fma_f32 v34, v174, v33, v34
	v_fma_f32 v2, -v173, v49, v2
	v_fma_f32 v18, -v175, v33, v18
	v_fma_f32 v50, v173, v1, v50
	v_fma_f32 v34, v175, v17, v34
	v_fma_f32 v3, v172, v2, v3
	v_fma_f32 v19, v174, v18, v19
	v_fma_f32 v51, v172, v50, v51
	v_fma_f32 v35, v174, v34, v35
	v_fma_f32 v3, -v173, v50, v3
	v_fma_f32 v19, -v175, v34, v19
	v_fma_f32 v51, v173, v2, v51
	v_fma_f32 v35, v175, v18, v35
	v_cvt_pk_bf16_f32 v190, v0, v1
	v_cvt_pk_bf16_f32 v191, v2, v3
	v_cvt_pk_bf16_f32 v192, v16, v17
	v_cvt_pk_bf16_f32 v193, v18, v19
	ds_write2st64_b64 v207, v[190:191], v[192:193] offset1:4
	v_cvt_pk_bf16_f32 v212, v48, v49
	v_cvt_pk_bf16_f32 v213, v50, v51
	v_cvt_pk_bf16_f32 v214, v32, v33
	v_cvt_pk_bf16_f32 v215, v34, v35
	ds_write2st64_b64 v207, v[212:213], v[214:215] offset0:8 offset1:12
	v_fma_f32 v4, v172, v3, v4
	v_fma_f32 v20, v174, v19, v20
	v_fma_f32 v52, v172, v51, v52
	v_fma_f32 v36, v174, v35, v36
	v_fma_f32 v4, -v173, v51, v4
	v_fma_f32 v20, -v175, v35, v20
	v_fma_f32 v52, v173, v3, v52
	v_fma_f32 v36, v175, v19, v36
	v_fma_f32 v5, v172, v4, v5
	v_fma_f32 v21, v174, v20, v21
	v_fma_f32 v53, v172, v52, v53
	v_fma_f32 v37, v174, v36, v37
	v_fma_f32 v5, -v173, v52, v5
	v_fma_f32 v21, -v175, v36, v21
	v_fma_f32 v53, v173, v4, v53
	v_fma_f32 v37, v175, v20, v37
	v_fma_f32 v6, v172, v5, v6
	v_fma_f32 v22, v174, v21, v22
	v_fma_f32 v54, v172, v53, v54
	v_fma_f32 v38, v174, v37, v38
	v_fma_f32 v6, -v173, v53, v6
	v_fma_f32 v22, -v175, v37, v22
	v_fma_f32 v54, v173, v5, v54
	v_fma_f32 v38, v175, v21, v38
	v_fma_f32 v7, v172, v6, v7
	v_fma_f32 v23, v174, v22, v23
	v_fma_f32 v55, v172, v54, v55
	v_fma_f32 v39, v174, v38, v39
	v_fma_f32 v7, -v173, v54, v7
	v_fma_f32 v23, -v175, v38, v23
	v_fma_f32 v55, v173, v6, v55
	v_fma_f32 v39, v175, v22, v39
	v_cvt_pk_bf16_f32 v190, v4, v5
	v_cvt_pk_bf16_f32 v191, v6, v7
	v_cvt_pk_bf16_f32 v192, v20, v21
	v_cvt_pk_bf16_f32 v193, v22, v23
	ds_write2st64_b64 v208, v[190:191], v[192:193] offset1:4
	v_cvt_pk_bf16_f32 v212, v52, v53
	v_cvt_pk_bf16_f32 v213, v54, v55
	v_cvt_pk_bf16_f32 v214, v36, v37
	v_cvt_pk_bf16_f32 v215, v38, v39
	ds_write2st64_b64 v208, v[212:213], v[214:215] offset0:8 offset1:12
	v_fma_f32 v8, v172, v7, v8
	v_fma_f32 v24, v174, v23, v24
	v_fma_f32 v56, v172, v55, v56
	v_fma_f32 v40, v174, v39, v40
	v_fma_f32 v8, -v173, v55, v8
	v_fma_f32 v24, -v175, v39, v24
	v_fma_f32 v56, v173, v7, v56
	v_fma_f32 v40, v175, v23, v40
	v_fma_f32 v9, v172, v8, v9
	v_fma_f32 v25, v174, v24, v25
	v_fma_f32 v57, v172, v56, v57
	v_fma_f32 v41, v174, v40, v41
	v_fma_f32 v9, -v173, v56, v9
	v_fma_f32 v25, -v175, v40, v25
	v_fma_f32 v57, v173, v8, v57
	v_fma_f32 v41, v175, v24, v41
	v_fma_f32 v10, v172, v9, v10
	v_fma_f32 v26, v174, v25, v26
	v_fma_f32 v58, v172, v57, v58
	v_fma_f32 v42, v174, v41, v42
	v_fma_f32 v10, -v173, v57, v10
	v_fma_f32 v26, -v175, v41, v26
	v_fma_f32 v58, v173, v9, v58
	v_fma_f32 v42, v175, v25, v42
	v_fma_f32 v11, v172, v10, v11
	v_fma_f32 v27, v174, v26, v27
	v_fma_f32 v59, v172, v58, v59
	v_fma_f32 v43, v174, v42, v43
	v_fma_f32 v11, -v173, v58, v11
	v_fma_f32 v27, -v175, v42, v27
	v_fma_f32 v59, v173, v10, v59
	v_fma_f32 v43, v175, v26, v43
	v_cvt_pk_bf16_f32 v190, v8, v9
	v_cvt_pk_bf16_f32 v191, v10, v11
	v_cvt_pk_bf16_f32 v192, v24, v25
	v_cvt_pk_bf16_f32 v193, v26, v27
	ds_write2st64_b64 v209, v[190:191], v[192:193] offset1:4
	v_cvt_pk_bf16_f32 v212, v56, v57
	v_cvt_pk_bf16_f32 v213, v58, v59
	v_cvt_pk_bf16_f32 v214, v40, v41
	v_cvt_pk_bf16_f32 v215, v42, v43
	ds_write2st64_b64 v209, v[212:213], v[214:215] offset0:8 offset1:12
	v_fma_f32 v12, v172, v11, v12
	v_fma_f32 v28, v174, v27, v28
	v_fma_f32 v60, v172, v59, v60
	v_fma_f32 v44, v174, v43, v44
	v_fma_f32 v12, -v173, v59, v12
	v_fma_f32 v28, -v175, v43, v28
	v_fma_f32 v60, v173, v11, v60
	v_fma_f32 v44, v175, v27, v44
	v_fma_f32 v13, v172, v12, v13
	v_fma_f32 v29, v174, v28, v29
	v_fma_f32 v61, v172, v60, v61
	v_fma_f32 v45, v174, v44, v45
	v_fma_f32 v13, -v173, v60, v13
	v_fma_f32 v29, -v175, v44, v29
	v_fma_f32 v61, v173, v12, v61
	v_fma_f32 v45, v175, v28, v45
	v_fma_f32 v14, v172, v13, v14
	v_fma_f32 v30, v174, v29, v30
	v_fma_f32 v62, v172, v61, v62
	v_fma_f32 v46, v174, v45, v46
	v_fma_f32 v14, -v173, v61, v14
	v_fma_f32 v30, -v175, v45, v30
	v_fma_f32 v62, v173, v13, v62
	v_fma_f32 v46, v175, v29, v46
	v_fma_f32 v15, v172, v14, v15
	v_fma_f32 v31, v174, v30, v31
	v_fma_f32 v63, v172, v62, v63
	v_fma_f32 v47, v174, v46, v47
	v_fma_f32 v15, -v173, v62, v15
	v_fma_f32 v31, -v175, v46, v31
	v_fma_f32 v63, v173, v14, v63
	v_fma_f32 v47, v175, v30, v47
	v_mov_b32_e32 v186, v15
	v_mov_b32_e32 v187, v63
	v_mov_b32_e32 v188, v31
	v_mov_b32_e32 v189, v47
	v_cvt_pk_bf16_f32 v190, v12, v13
	v_cvt_pk_bf16_f32 v191, v14, v15
	v_cvt_pk_bf16_f32 v192, v28, v29
	v_cvt_pk_bf16_f32 v193, v30, v31
	ds_write2st64_b64 v210, v[190:191], v[192:193] offset1:4
	v_cvt_pk_bf16_f32 v212, v60, v61
	v_cvt_pk_bf16_f32 v213, v62, v63
	v_cvt_pk_bf16_f32 v214, v44, v45
	v_cvt_pk_bf16_f32 v215, v46, v47
	ds_write2st64_b64 v210, v[212:213], v[214:215] offset0:8 offset1:12
	s_waitcnt lgkmcnt(0)
	ds_read_b64_tr_b16 v[0:1], v151 offset:0
	ds_read_b64_tr_b16 v[2:3], v199 offset:0
	ds_read_b64_tr_b16 v[28:29], v151 offset:1024
	ds_read_b64_tr_b16 v[30:31], v199 offset:1024
	ds_read_b64_tr_b16 v[24:25], v151 offset:2048
	ds_read_b64_tr_b16 v[26:27], v199 offset:2048
	ds_read_b64_tr_b16 v[20:21], v151 offset:3072
	ds_read_b64_tr_b16 v[22:23], v199 offset:3072
	ds_read_b64_tr_b16 v[16:17], v151 offset:4096
	ds_read_b64_tr_b16 v[18:19], v199 offset:4096
	ds_read_b64_tr_b16 v[44:45], v151 offset:5120
	ds_read_b64_tr_b16 v[46:47], v199 offset:5120
	ds_read_b64_tr_b16 v[40:41], v151 offset:6144
	ds_read_b64_tr_b16 v[42:43], v199 offset:6144
	ds_read_b64_tr_b16 v[52:53], v151 offset:7168
	ds_read_b64_tr_b16 v[54:55], v199 offset:7168
	s_waitcnt lgkmcnt(0)
	s_nop 0
	v_mfma_f32_32x32x16_bf16 v[0:15], v[68:71], v[0:3], 0
	v_mfma_f32_32x32x16_bf16 v[0:15], v[64:67], v[28:31], v[0:15]
	v_mfma_f32_32x32x16_bf16 v[0:15], v[76:79], v[24:27], v[0:15]
	v_mfma_f32_32x32x16_bf16 v[0:15], v[72:75], v[20:23], v[0:15]
	v_mfma_f32_32x32x16_bf16 v[0:15], v[84:87], v[16:19], v[0:15]
	v_mfma_f32_32x32x16_bf16 v[0:15], v[80:83], v[44:47], v[0:15]
	v_mfma_f32_32x32x16_bf16 v[0:15], v[92:95], v[40:43], v[0:15]
	v_mfma_f32_32x32x16_bf16 v[0:15], v[88:91], v[52:55], v[0:15]
	s_and_saveexec_b64 s[2:3], s[52:53]
	s_cbranch_execz .LBB0_186
	s_nop 7
	v_add_u32_e32 v16, v200, v146
	v_add_u32_e32 v16, 0x2000, v16
	ds_read2_b64 v[16:19], v16 offset1:2
	s_waitcnt lgkmcnt(0)
	v_lshlrev_b32_e32 v10, 16, v19
	v_and_b32_e32 v11, 0xffff0000, v19
	v_pk_fma_f32 v[6:7], v[102:103], v[10:11], v[6:7]
	s_nop 0
	v_mul_f32_e32 v10, v7, v7
	v_fmaak_f32 v10, v240, v10, 0xc0135761
	v_mul_f32_e32 v11, v6, v6
	v_mul_f32_e32 v10, v7, v10
	v_fmaak_f32 v11, v240, v11, 0xc0135761
	v_mul_f32_e32 v11, v6, v11
	v_exp_f32_e32 v10, v10
	v_exp_f32_e32 v11, v11
	v_add_f32_e32 v8, 1.0, v10
	v_rcp_f32_e32 v9, v8
	v_add_f32_e32 v8, 1.0, v11
	v_lshlrev_b32_e32 v10, 16, v18
	v_and_b32_e32 v11, 0xffff0000, v18
	v_pk_fma_f32 v[4:5], v[100:101], v[10:11], v[4:5]
	v_and_b32_e32 v13, 0xffff0000, v17
	v_mul_f32_e32 v10, v5, v5
	v_fmaak_f32 v10, v240, v10, 0xc0135761
	v_mul_f32_e32 v11, v4, v4
	v_mul_f32_e32 v10, v5, v10
	v_fmaak_f32 v11, v240, v11, 0xc0135761
	v_mul_f32_e32 v11, v4, v11
	v_exp_f32_e32 v10, v10
	v_exp_f32_e32 v12, v11
	v_and_b32_e32 v15, 0xffff0000, v16
	v_add_f32_e32 v10, 1.0, v10
	v_rcp_f32_e32 v11, v10
	v_add_f32_e32 v10, 1.0, v12
	v_lshlrev_b32_e32 v12, 16, v17
	v_pk_fma_f32 v[2:3], v[98:99], v[12:13], v[2:3]
	v_rcp_f32_e32 v8, v8
	v_mul_f32_e32 v12, v3, v3
	v_fmaak_f32 v12, v240, v12, 0xc0135761
	v_mul_f32_e32 v13, v2, v2
	v_mul_f32_e32 v12, v3, v12
	v_fmaak_f32 v13, v240, v13, 0xc0135761
	v_mul_f32_e32 v13, v2, v13
	v_exp_f32_e32 v12, v12
	v_exp_f32_e32 v14, v13
	s_cmp_eq_u32 s24, -3
	v_add_f32_e32 v12, 1.0, v12
	v_rcp_f32_e32 v13, v12
	v_add_f32_e32 v12, 1.0, v14
	v_lshlrev_b32_e32 v14, 16, v16
	v_pk_fma_f32 v[0:1], v[96:97], v[14:15], v[0:1]
	v_rcp_f32_e32 v12, v12
	v_mul_f32_e32 v14, v1, v1
	v_fmaak_f32 v14, v240, v14, 0xc0135761
	v_mul_f32_e32 v15, v0, v0
	v_mul_f32_e32 v14, v1, v14
	v_fmaak_f32 v15, v240, v15, 0xc0135761
	v_mul_f32_e32 v15, v0, v15
	v_exp_f32_e32 v14, v14
	v_exp_f32_e32 v16, v15
	v_rcp_f32_e32 v10, v10
	v_add_f32_e32 v14, 1.0, v14
	v_rcp_f32_e32 v15, v14
	v_add_f32_e32 v14, 1.0, v16
	v_rcp_f32_e32 v14, v14
	s_cselect_b64 vcc, -1, 0
	s_ashr_i32 s15, s14, 31
	v_pk_mul_f32 v[6:7], v[6:7], v[8:9]
	v_lshl_add_u64 v[8:9], s[14:15], 4, v[120:121]
	v_cndmask_b32_e64 v9, v9, 0, vcc
	v_cndmask_b32_e32 v8, v8, v154, vcc
	v_pk_mul_f32 v[2:3], v[2:3], v[12:13]
	v_pk_mul_f32 v[0:1], v[0:1], v[14:15]
	v_lshlrev_b64 v[8:9], 11, v[8:9]
	v_pk_mul_f32 v[4:5], v[4:5], v[10:11]
	v_lshl_add_u64 v[8:9], v[126:127], 0, v[8:9]
	v_cvt_pk_bf16_f32 v0, v0, v1
	v_cvt_pk_bf16_f32 v1, v2, v3
	v_cvt_pk_bf16_f32 v2, v4, v5
	v_cvt_pk_bf16_f32 v3, v6, v7
	global_store_dwordx2 v[8:9], v[0:1], off
	global_store_dwordx2 v[8:9], v[2:3], off offset:16
	s_branch .LBB0_186
